# attention work queue: next item dequeued one item ahead by lane 0 (atomic round trip overlaps the item prologue)
# baseline (speedup 1.0000x reference)
.LBB0_830:
	s_cmp_lt_i32 s8, 6
	s_cselect_b64 s[0:1], -1, 0
	s_cmp_gt_i32 s9, 5
	s_cselect_b64 s[2:3], -1, 0
	s_and_b64 s[0:1], s[0:1], s[2:3]
	s_andn2_b64 vcc, exec, s[0:1]
	s_cbranch_vccnz .LBB0_873
	v_and_b32_e32 v1, 63, v144
	v_readlane_b32 s36, v254, 29
	v_lshlrev_b32_e32 v8, 2, v1
	v_readlane_b32 s48, v254, 41
	v_readlane_b32 s49, v254, 42
	v_readlane_b32 s50, v254, 43
	v_readlane_b32 s51, v254, 44
	s_nop 2
	global_load_dword v9, v8, s[48:49]
	s_nop 0
	global_load_dword v10, v8, s[50:51]
	v_readlane_b32 s4, v254, 0
	v_readlane_b32 s5, v254, 1
	v_readlane_b32 s6, v254, 2
	v_readlane_b32 s7, v254, 3
	s_nop 2
	global_load_dword v11, v8, s[4:5]
	s_nop 0
	global_load_dword v12, v8, s[6:7]
	v_readlane_b32 s40, v254, 33
	v_readlane_b32 s41, v254, 34
	v_mbcnt_lo_u32_b32 v0, -1, 0
	v_mbcnt_hi_u32_b32 v0, -1, v0
	v_and_b32_e32 v2, 64, v0
	v_add_u32_e32 v2, 64, v2
	v_xor_b32_e32 v4, 32, v0
	global_load_dword v21, v8, s[40:41]
	v_cmp_lt_i32_e32 vcc, v4, v2
	v_cmp_gt_u32_e64 s[6:7], 32, v1
	v_lshrrev_b32_e32 v19, 7, v144
	v_cndmask_b32_e32 v4, v0, v4, vcc
	v_lshlrev_b32_e32 v115, 2, v4
	v_xor_b32_e32 v4, 16, v0
	v_cmp_lt_i32_e32 vcc, v4, v2
	v_and_b32_e32 v5, 31, v144
	v_lshlrev_b32_e32 v145, 5, v19
	v_cndmask_b32_e32 v4, v0, v4, vcc
	v_lshlrev_b32_e32 v13, 2, v4
	v_xor_b32_e32 v4, 8, v0
	v_cmp_lt_i32_e32 vcc, v4, v2
	v_or_b32_e32 v150, v145, v5
	v_lshlrev_b32_e32 v152, 8, v5
	v_cndmask_b32_e32 v4, v0, v4, vcc
	v_lshlrev_b32_e32 v14, 2, v4
	v_xor_b32_e32 v4, 4, v0
	v_cmp_lt_i32_e32 vcc, v4, v2
	v_lshlrev_b32_e32 v153, 7, v5
	v_lshlrev_b32_e32 v5, 14, v19
	v_cndmask_b32_e32 v4, v0, v4, vcc
	v_lshlrev_b32_e32 v15, 2, v4
	v_xor_b32_e32 v4, 2, v0
	v_cmp_lt_i32_e32 vcc, v4, v2
	v_bfe_u32 v7, v144, 6, 1
	v_add3_u32 v154, 0, v5, v8
	v_cndmask_b32_e32 v4, v0, v4, vcc
	v_lshlrev_b32_e32 v16, 2, v4
	v_xor_b32_e32 v4, 1, v0
	v_lshrrev_b32_e32 v3, 6, v144
	v_cmp_lt_i32_e32 vcc, v4, v2
	v_bfe_u32 v18, v144, 5, 1
	v_and_b32_e32 v24, 15, v144
	v_lshlrev_b32_e32 v29, 3, v7
	v_cndmask_b32_e32 v0, v0, v4, vcc
	v_lshlrev_b32_e32 v4, 2, v3
	v_lshlrev_b32_e32 v6, 3, v3
	v_lshl_add_u32 v155, v3, 10, 0
	v_bitop3_b32 v3, v29, v24, v18 bitop3:0x36
	v_lshlrev_b32_e32 v156, 4, v3
	v_or_b32_e32 v30, v29, v18
	v_lshlrev_b32_e32 v17, 2, v0
	v_lshlrev_b32_e32 v0, 6, v7
	v_cmp_eq_u32_e64 s[4:5], 0, v7
	v_bitop3_b32 v7, v30, v24, 2 bitop3:0x36
	v_lshlrev_b32_e32 v157, 4, v7
	v_bitop3_b32 v7, v30, v24, 4 bitop3:0x36
	v_lshlrev_b32_e32 v158, 4, v7
	v_bitop3_b32 v7, v30, v24, 6 bitop3:0x36
	v_lshlrev_b32_e32 v159, 4, v7
	v_lshrrev_b32_e32 v27, 1, v144
	v_bfe_u32 v28, v144, 1, 3
	s_mov_b32 s0, 0x3fb8aa3b
	s_add_u32 s14, s90, 0x14948000
	s_addc_u32 s15, s91, 0
	v_readlane_b32 s8, v254, 4
	v_readlane_b32 s9, v254, 5
	v_mov_b32_e32 v113, 0
	v_lshlrev_b32_e32 v112, 4, v18
	s_mov_b32 s1, 0xc2ce8ed0
	s_add_u32 s16, s90, 0xf0f0000
	v_lshl_add_u64 v[118:119], s[8:9], 0, v[112:113]
	s_mov_b32 s8, 0x42b17218
	s_addc_u32 s17, s91, 0
	s_add_u32 s18, s90, 0x1bf98400
	s_waitcnt vmcnt(3)
	v_mul_f32_e32 v1, v9, v10
	ds_bpermute_b32 v1, v115, v1
	s_addc_u32 s19, s91, 0
	s_add_u32 s20, s90, 0x4040000
	s_addc_u32 s21, s91, 0
	s_waitcnt vmcnt(1)
	v_mul_f32_e32 v3, v11, v12
	s_waitcnt lgkmcnt(0)
	v_fmac_f32_e32 v1, v9, v10
	ds_bpermute_b32 v5, v13, v1
	ds_bpermute_b32 v3, v115, v3
	v_bfe_u32 v26, v144, 3, 3
	s_add_u32 s22, s90, 0x9898000
	v_lshrrev_b32_e32 v2, 5, v144
	s_waitcnt lgkmcnt(1)
	v_add_f32_e32 v1, v1, v5
	ds_bpermute_b32 v9, v14, v1
	s_waitcnt lgkmcnt(1)
	v_fmac_f32_e32 v3, v11, v12
	ds_bpermute_b32 v5, v13, v3
	v_or_b32_e32 v151, v6, v26
	s_addc_u32 s23, s91, 0
	s_waitcnt lgkmcnt(1)
	v_add_f32_e32 v1, v1, v9
	ds_bpermute_b32 v7, v15, v1
	s_waitcnt lgkmcnt(1)
	v_add_f32_e32 v3, v3, v5
	ds_bpermute_b32 v5, v14, v3
	v_bitop3_b32 v9, v18, v27, 7 bitop3:0x78
	v_lshlrev_b32_e32 v160, 4, v9
	s_waitcnt lgkmcnt(1)
	v_add_f32_e32 v1, v1, v7
	ds_bpermute_b32 v7, v16, v1
	s_waitcnt lgkmcnt(1)
	v_add_f32_e32 v3, v3, v5
	ds_bpermute_b32 v5, v15, v3
	v_bitop3_b32 v9, v18, v28, 2 bitop3:0x36
	v_lshlrev_b32_e32 v161, 4, v9
	s_waitcnt lgkmcnt(1)
	v_add_f32_e32 v1, v1, v7
	ds_bpermute_b32 v7, v17, v1
	s_waitcnt lgkmcnt(1)
	v_add_f32_e32 v3, v3, v5
	ds_bpermute_b32 v5, v16, v3
	v_bitop3_b32 v9, v18, v28, 4 bitop3:0x36
	v_lshlrev_b32_e32 v162, 4, v9
	s_waitcnt lgkmcnt(1)
	v_add_f32_e32 v1, v1, v7
	v_bitop3_b32 v9, v18, v28, 6 bitop3:0x36
	v_mul_f32_e32 v7, 0x3fb8aa3b, v1
	v_lshlrev_b32_e32 v163, 4, v9
	v_fma_f32 v9, v1, s0, -v7
	v_rndne_f32_e32 v10, v7
	v_fmac_f32_e32 v9, 0x32a5705f, v1
	v_sub_f32_e32 v7, v7, v10
	s_waitcnt lgkmcnt(0)
	v_add_f32_e32 v3, v3, v5
	v_add_f32_e32 v7, v7, v9
	v_cvt_i32_f32_e32 v9, v10
	s_waitcnt vmcnt(0)
	v_and_b32_e32 v10, 0x7fffffff, v21
	ds_bpermute_b32 v5, v17, v3
	ds_bpermute_b32 v10, v115, v10
	v_exp_f32_e32 v7, v7
	v_cmp_ngt_f32_e32 vcc, s1, v1
	v_bfe_u32 v20, v144, 4, 2
	s_waitcnt lgkmcnt(1)
	v_add_f32_e32 v3, v3, v5
	v_ldexp_f32 v5, v7, v9
	s_waitcnt lgkmcnt(0)
	v_max_f32_e32 v7, v10, v10
	v_max_f32_e64 v9, |v21|, |v21|
	v_max_f32_e32 v7, v9, v7
	ds_bpermute_b32 v9, v13, v7
	v_mul_f32_e32 v10, 0x3fb8aa3b, v3
	v_fma_f32 v11, v3, s0, -v10
	v_rndne_f32_e32 v12, v10
	v_fmac_f32_e32 v11, 0x32a5705f, v3
	s_waitcnt lgkmcnt(0)
	v_max_f32_e32 v9, v9, v9
	v_max_f32_e32 v7, v7, v9
	ds_bpermute_b32 v9, v14, v7
	v_sub_f32_e32 v10, v10, v12
	v_add_f32_e32 v10, v10, v11
	v_exp_f32_e32 v10, v10
	v_cvt_i32_f32_e32 v11, v12
	s_waitcnt lgkmcnt(0)
	v_max_f32_e32 v9, v9, v9
	v_max_f32_e32 v7, v7, v9
	ds_bpermute_b32 v9, v15, v7
	v_cndmask_b32_e32 v5, 0, v5, vcc
	v_mov_b32_e32 v12, 0x7f800000
	v_cmp_nlt_f32_e32 vcc, s8, v1
	v_and_b32_e32 v22, 8, v6
	s_waitcnt lgkmcnt(0)
	v_max_f32_e32 v9, v9, v9
	v_max_f32_e32 v7, v7, v9
	ds_bpermute_b32 v9, v16, v7
	v_cndmask_b32_e32 v1, v12, v5, vcc
	v_ldexp_f32 v5, v10, v11
	v_cmp_ngt_f32_e32 vcc, s1, v3
	v_and_b32_e32 v23, 4, v2
	s_waitcnt lgkmcnt(0)
	v_max_f32_e32 v9, v9, v9
	v_max_f32_e32 v7, v7, v9
	ds_bpermute_b32 v9, v17, v7
	v_cndmask_b32_e32 v5, 0, v5, vcc
	v_cmp_nlt_f32_e32 vcc, s8, v3
	v_lshrrev_b32_e32 v26, 1, v151
	s_add_u32 s24, s90, 0x18988000
	v_cndmask_b32_e32 v3, v12, v5, vcc
	v_sub_f32_e32 v1, v1, v3
	s_waitcnt lgkmcnt(0)
	v_max_f32_e32 v3, v9, v9
	v_max_f32_e32 v3, v7, v3
	v_add_f32_e32 v164, 0x3eb60549, v1
	v_mul_f32_e32 v1, 0x41000000, v3
	v_bitop3_b32 v25, v4, v24, v20 bitop3:0x36
	v_xor_b32_e32 v6, v26, v144
	v_mul_f32_e32 v165, 0x3f828f5c, v1
	v_or3_b32 v1, v20, v22, v23
	s_addc_u32 s25, s91, 0
	v_or3_b32 v2, v22, v23, v20
	v_lshlrev_b32_e32 v6, 3, v6
	v_lshl_add_u64 v[116:117], s[90:91], 0, v[112:113]
	v_lshlrev_b32_e32 v112, 11, v1
	v_lshlrev_b32_e32 v10, 4, v25
	v_mov_b32_e32 v11, v113
	s_mov_b64 s[12:13], src_shared_base
	v_readlane_b32 s37, v254, 30
	v_readlane_b32 s38, v254, 31
	v_readlane_b32 s39, v254, 32
	s_add_u32 s26, s90, 0x19a88000
	v_lshlrev_b32_e32 v2, 10, v2
	v_lshlrev_b32_e32 v4, 3, v25
	v_and_b32_e32 v6, 56, v6
	v_and_b32_e32 v19, 64, v144
	v_lshlrev_b32_e32 v8, 2, v18
	v_lshl_add_u64 v[10:11], v[112:113], 0, v[10:11]
	s_mov_b64 s[28:29], 0x20000
	v_bitop3_b32 v1, v26, 7, v144 bitop3:0x48
	v_mov_b32_e32 v3, 0x80
	s_addc_u32 s27, s91, 0
	v_lshlrev_b32_e32 v114, 3, v18
	v_cmp_ne_u32_e64 s[2:3], 0, v19
	s_mov_b32 s12, 0x41000000
	v_lshl_add_u64 v[120:121], v[10:11], 0, s[28:29]
	v_lshl_or_b32 v122, v1, 4, v3
	v_mov_b32_e32 v123, v113
	s_mov_b64 s[30:31], 0
	v_mov_b32_e32 v166, 1
	s_movk_i32 s52, 0x208
	s_movk_i32 s53, 0xfc0
	s_mov_b32 s54, 0x44000
	v_lshlrev_b32_e32 v124, 1, v0
	s_mov_b32 s55, 0x42480000
	s_mov_b64 s[34:35], 0x8000
	s_mov_b64 s[36:37], 0x10000
	s_mov_b64 s[38:39], 0x18000
	s_mov_b64 s[40:41], 0x80
	v_mov_b32_e32 v167, 0x358637bd
	s_mov_b32 s56, 0x800000
	v_lshlrev_b32_e32 v126, 1, v8
	s_mov_b32 s57, 0x8080
	v_mov_b32_e32 v168, 0x8000
	v_lshlrev_b32_e32 v128, 1, v2
	v_lshlrev_b32_e32 v130, 1, v4
	v_lshlrev_b32_e32 v132, 1, v6
	v_mov_b32_e32 v169, 0xff800000
	v_mov_b32_e32 v134, v199
	v_mov_b32_e32 v170, 0
	v_readlane_b32 s42, v254, 35
	v_readlane_b32 s43, v254, 36
	v_readlane_b32 s44, v254, 37
	v_readlane_b32 s45, v254, 38
	v_readlane_b32 s46, v254, 39
	v_readlane_b32 s47, v254, 40
	v_readlane_b32 s10, v254, 6
	v_readlane_b32 s11, v254, 7
	s_mov_b64 s[62:63], exec
	v_readlane_b32 s64, v254, 11
	v_readlane_b32 s65, v254, 12
	s_and_b64 s[64:65], s[62:63], s[64:65]
	s_mov_b64 exec, s[64:65]
	s_cbranch_execz .Lpf_c
	v_mov_b32_e32 v219, v113
	v_mov_b32_e32 v218, v134
	v_lshl_add_u64 v[218:219], v[218:219], 2, s[18:19]
	global_atomic_add v216, v[218:219], v166, off sc0
.Lpf_c:
	s_mov_b64 exec, s[62:63]
	s_branch .LBB0_833

.LBB0_833:
	s_mov_b64 s[0:1], exec
	v_readlane_b32 s8, v254, 11
	v_readlane_b32 s9, v254, 12
	s_and_b64 s[8:9], s[0:1], s[8:9]
	s_mov_b64 exec, s[8:9]
	s_cbranch_execz .LBB0_835
	v_mov_b32_e32 v135, v113
	v_lshl_add_u64 v[0:1], v[134:135], 2, s[18:19]
	s_mov_b64 s[8:9], src_shared_base
	s_add_i32 s8, 0, 0x10000
	s_cmp_lg_u32 s8, -1
	s_cselect_b32 s8, s8, 0
	s_cselect_b32 s9, s9, 0
	v_mov_b32_e32 v0, s8
	v_mov_b32_e32 v1, s9
	s_waitcnt vmcnt(0)
	flat_store_dword v[0:1], v216 sc0 sc1
	s_waitcnt vmcnt(0)

.LBB0_840:
	s_or_b64 exec, exec, s[0:1]
	s_mov_b64 s[62:63], exec
	v_readlane_b32 s64, v254, 11
	v_readlane_b32 s65, v254, 12
	s_and_b64 s[64:65], s[62:63], s[64:65]
	s_mov_b64 exec, s[64:65]
	s_cbranch_execz .Lpf_a
	v_mov_b32_e32 v219, v113
	v_mov_b32_e32 v218, v134
	v_lshl_add_u64 v[218:219], v[218:219], 2, s[18:19]
	global_atomic_add v216, v[218:219], v166, off sc0
.Lpf_a:
	s_mov_b64 exec, s[62:63]
	v_add_u32_e32 v136, v6, v150
	v_min_i32_e32 v112, 0x807f, v136
	v_lshlrev_b64 v[6:7], 11, v[112:113]
	v_lshl_add_u64 v[6:7], s[16:17], 0, v[6:7]
	v_lshl_add_u64 v[6:7], v[138:139], 1, v[6:7]
	v_mov_b32_e32 v125, v113
	v_lshl_add_u64 v[6:7], v[6:7], 0, v[124:125]
	v_lshlrev_b32_e32 v112, 1, v114
	v_lshl_add_u64 v[6:7], v[6:7], 0, v[112:113]
	global_load_dwordx4 v[96:99], v[6:7], off
	global_load_dwordx4 v[100:103], v[6:7], off offset:32
	global_load_dwordx4 v[104:107], v[6:7], off offset:64
	global_load_dwordx4 v[108:111], v[6:7], off offset:96
	v_readfirstlane_b32 s98, v0
	v_readfirstlane_b32 s99, v1
	v_readfirstlane_b32 s100, v2
	v_readfirstlane_b32 s101, v3
	v_mov_b32_e32 v129, v113
	v_mul_u32_u24_e32 v5, v4, v151
	v_lshl_add_u64 v[6:7], v[0:1], 0, v[128:129]
	v_mov_b32_e32 v131, v113
	v_lshlrev_b32_e32 v8, 1, v5
	v_mov_b32_e32 v9, v113
	v_readfirstlane_b32 s0, v155
	v_add_u32_e32 v5, 0x4000, v155
	v_lshl_add_u64 v[6:7], v[6:7], 0, v[130:131]
	v_lshl_add_u64 v[10:11], v[2:3], 0, v[8:9]
	v_mov_b32_e32 v133, v113
	s_mov_b32 m0, s0
	v_readfirstlane_b32 s0, v5
	v_add_u32_e32 v5, 0x1000, v155
	v_lshl_add_u64 v[10:11], v[10:11], 0, v[132:133]
	global_load_lds_dwordx4 v[6:7], off
	s_mov_b32 m0, s0
	v_readfirstlane_b32 s0, v5
	v_add_u32_e32 v5, 0x5000, v155
	global_load_lds_dwordx4 v[10:11], off
	v_lshl_add_u64 v[12:13], v[6:7], 0, s[34:35]
	s_mov_b32 m0, s0
	v_lshlrev_b32_e32 v112, 6, v4
	v_readfirstlane_b32 s0, v5
	v_add_u32_e32 v5, 0x2000, v155
	global_load_lds_dwordx4 v[12:13], off
	v_lshl_add_u64 v[10:11], v[10:11], 0, v[112:113]
	s_mov_b32 m0, s0
	v_readfirstlane_b32 s0, v5
	v_add_u32_e32 v5, 0x6000, v155
	global_load_lds_dwordx4 v[10:11], off
	v_lshl_add_u64 v[12:13], v[6:7], 0, s[36:37]
	s_mov_b32 m0, s0
	v_readfirstlane_b32 s0, v5
	v_add_u32_e32 v5, 0x3000, v155
	global_load_lds_dwordx4 v[12:13], off
	v_lshl_add_u64 v[10:11], v[10:11], 0, v[112:113]
	s_mov_b32 m0, s0
	v_readfirstlane_b32 s0, v5
	v_add_u32_e32 v5, 0x7000, v155
	global_load_lds_dwordx4 v[10:11], off
	v_lshl_add_u64 v[6:7], v[6:7], 0, s[38:39]
	s_mov_b32 m0, s0
	v_readfirstlane_b32 s0, v5
	global_load_lds_dwordx4 v[6:7], off
	v_lshl_add_u64 v[6:7], v[10:11], 0, v[112:113]
	s_mov_b32 m0, s0
	v_lshl_add_u64 v[140:141], v[0:1], 0, v[120:121]
	global_load_lds_dwordx4 v[6:7], off
	v_lshl_add_u64 v[0:1], v[2:3], 0, v[122:123]
	v_mov_b32_e32 v14, v113
	v_mov_b32_e32 v15, v113
	v_lshl_add_u64 v[142:143], v[0:1], 0, v[8:9]
	v_lshlrev_b32_e32 v146, 7, v4
	v_mul_hi_u32_u24_e32 v149, 0xc0, v4
	v_mul_u32_u24_e32 v148, 0xc0, v4
	v_mov_b32_e32 v172, 0
	s_mov_b64 s[44:45], 0
	s_mov_b64 s[8:9], 0
	v_mov_b32_e32 v125, 0
	s_and_saveexec_b64 s[0:1], vcc
	s_cbranch_execz .LBB0_842
	s_waitcnt vmcnt(11)
	v_and_b32_e32 v6, 0xffff0000, v96
	v_lshlrev_b32_e32 v5, 16, v96
	v_mul_f32_e32 v8, v6, v6
	v_fmac_f32_e32 v8, v5, v5
	v_lshlrev_b32_e32 v5, 16, v97
	v_fmac_f32_e32 v8, v5, v5
	v_and_b32_e32 v5, 0xffff0000, v97
	v_fmac_f32_e32 v8, v5, v5
	v_lshlrev_b32_e32 v5, 16, v98
	v_fmac_f32_e32 v8, v5, v5
	v_and_b32_e32 v5, 0xffff0000, v98
	v_fmac_f32_e32 v8, v5, v5
	v_lshlrev_b32_e32 v5, 16, v99
	v_fmac_f32_e32 v8, v5, v5
	v_and_b32_e32 v5, 0xffff0000, v99
	v_fmac_f32_e32 v8, v5, v5
	s_waitcnt vmcnt(10)
	v_lshlrev_b32_e32 v5, 16, v100
	v_fmac_f32_e32 v8, v5, v5
	v_and_b32_e32 v5, 0xffff0000, v100
	v_fmac_f32_e32 v8, v5, v5
	v_lshlrev_b32_e32 v5, 16, v101
	v_fmac_f32_e32 v8, v5, v5
	v_and_b32_e32 v5, 0xffff0000, v101
	v_fmac_f32_e32 v8, v5, v5
	v_lshlrev_b32_e32 v5, 16, v102
	v_fmac_f32_e32 v8, v5, v5
	v_and_b32_e32 v5, 0xffff0000, v102
	v_fmac_f32_e32 v8, v5, v5
	v_lshlrev_b32_e32 v5, 16, v103
	v_fmac_f32_e32 v8, v5, v5
	v_and_b32_e32 v5, 0xffff0000, v103
	v_fmac_f32_e32 v8, v5, v5
	s_waitcnt vmcnt(9)
	v_lshlrev_b32_e32 v5, 16, v104
	v_fmac_f32_e32 v8, v5, v5
	v_and_b32_e32 v5, 0xffff0000, v104
	v_fmac_f32_e32 v8, v5, v5
	v_lshlrev_b32_e32 v5, 16, v105
	v_fmac_f32_e32 v8, v5, v5
	v_and_b32_e32 v5, 0xffff0000, v105
	v_fmac_f32_e32 v8, v5, v5
	v_lshlrev_b32_e32 v5, 16, v106
	v_fmac_f32_e32 v8, v5, v5
	v_and_b32_e32 v5, 0xffff0000, v106
	v_fmac_f32_e32 v8, v5, v5
	v_lshlrev_b32_e32 v5, 16, v107
	v_fmac_f32_e32 v8, v5, v5
	v_and_b32_e32 v5, 0xffff0000, v107
	s_waitcnt vmcnt(8)
	v_and_b32_e32 v7, 0xffff0000, v108
	v_lshlrev_b32_e32 v6, 16, v108
	v_fmac_f32_e32 v8, v5, v5
	v_pk_mul_f32 v[6:7], v[6:7], v[6:7]
	s_nop 0
	v_add_f32_e32 v5, v6, v8
	v_add_f32_e32 v5, v7, v5
	v_and_b32_e32 v7, 0xffff0000, v109
	v_lshlrev_b32_e32 v6, 16, v109
	v_pk_mul_f32 v[6:7], v[6:7], v[6:7]
	s_nop 0
	v_add_f32_e32 v5, v6, v5
	v_add_f32_e32 v5, v7, v5
	v_and_b32_e32 v7, 0xffff0000, v110
	v_lshlrev_b32_e32 v6, 16, v110
	v_pk_mul_f32 v[6:7], v[6:7], v[6:7]
	s_nop 0
	v_add_f32_e32 v5, v6, v5
	v_add_f32_e32 v5, v7, v5
	v_and_b32_e32 v7, 0xffff0000, v111
	v_lshlrev_b32_e32 v6, 16, v111
	v_pk_mul_f32 v[6:7], v[6:7], v[6:7]
	s_nop 0
	v_add_f32_e32 v5, v6, v5
	v_add_f32_e32 v5, v7, v5
	ds_bpermute_b32 v6, v115, v5
	s_waitcnt lgkmcnt(0)
	v_add_f32_e32 v5, v5, v6
	v_sqrt_f32_e32 v5, v5
	s_nop 0
	v_fmaak_f32 v5, v165, v5, 0x3d4ccccd
	v_cmp_lt_f32_e32 vcc, s55, v5
	s_cmp_eq_u64 vcc, 0
	s_cselect_b64 vcc, -1, 0
	v_cndmask_b32_e32 v125, 0, v5, vcc
	s_and_b64 s[8:9], vcc, exec

.LBB0_861:
	s_andn2_saveexec_b64 s[0:1], s[42:43]
	s_cbranch_execz .LBB0_832
	v_add_u32_e32 v0, 1, v134
	v_and_b32_e32 v134, 7, v0
	s_mov_b64 s[62:63], exec
	v_readlane_b32 s64, v254, 11
	v_readlane_b32 s65, v254, 12
	s_and_b64 s[64:65], s[62:63], s[64:65]
	s_mov_b64 exec, s[64:65]
	s_cbranch_execz .Lpf_b
	v_mov_b32_e32 v219, v113
	v_mov_b32_e32 v218, v134
	v_lshl_add_u64 v[218:219], v[218:219], 2, s[18:19]
	global_atomic_add v216, v[218:219], v166, off sc0
.Lpf_b:
	s_mov_b64 exec, s[62:63]
	v_add_u32_e32 v170, 1, v170
	s_branch .LBB0_832
